# lever 2 on the PLE gate epilogue: xb and pe loads kept 10 chunks in flight with counted vmcnt instead of 32 serial round trips per tile
# speedup vs baseline: 1.0079x; 1.0079x over previous
.LBB0_102:
	s_add_u32 s22, s20, 0xfff80080
	s_addc_u32 s23, s21, -1
	s_add_i32 s44, 0, 0x10000
	v_add_u32_e32 v144, s44, v147
	ds_read_b128 v[136:139], v144
	ds_read_b128 v[140:143], v144 offset:1024
	ds_read_b128 v[150:153], v144 offset:2048
	ds_read_b128 v[154:157], v144 offset:3072
	s_cmp_eq_u32 s43, 28
	s_cselect_b32 s25, s13, s23
	s_cselect_b32 s24, s39, s22
	s_cselect_b32 s23, s11, s42
	s_cselect_b32 s22, s40, s41
	v_lshl_add_u64 v[144:145], s[20:21], 0, v[132:133]
	s_add_i32 m0, s19, 0xc000
	ds_read_b128 v[158:161], v149
	ds_read_b128 v[176:179], v149 offset:1024
	ds_read_b128 v[180:183], v149 offset:2048
	ds_read_b128 v[184:187], v149 offset:3072
	ds_read_b128 v[188:191], v149 offset:4096
	ds_read_b128 v[192:195], v149 offset:5120
	ds_read_b128 v[208:211], v149 offset:6144
	ds_read_b128 v[212:215], v149 offset:7168
	global_load_lds_dwordx4 v[144:145], off
	v_lshl_add_u64 v[144:145], s[20:21], 0, v[134:135]
	s_add_i32 m0, s19, 0xe000
	s_nop 0
	global_load_lds_dwordx4 v[144:145], off
	s_waitcnt lgkmcnt(8)
	s_barrier
	s_waitcnt lgkmcnt(0)
	s_setprio 1
	s_waitcnt lgkmcnt(0)
	v_mfma_f32_16x16x32_bf16 v[124:127], v[136:139], v[158:161], v[124:127]
	v_mfma_f32_16x16x32_bf16 v[120:123], v[150:153], v[158:161], v[120:123]
	v_mfma_f32_16x16x32_bf16 v[108:111], v[136:139], v[180:183], v[108:111]
	v_mfma_f32_16x16x32_bf16 v[104:107], v[150:153], v[180:183], v[104:107]
	v_mfma_f32_16x16x32_bf16 v[92:95], v[136:139], v[188:191], v[92:95]
	v_mfma_f32_16x16x32_bf16 v[88:91], v[150:153], v[188:191], v[88:91]
	v_mfma_f32_16x16x32_bf16 v[76:79], v[136:139], v[208:211], v[76:79]
	v_mfma_f32_16x16x32_bf16 v[72:75], v[150:153], v[208:211], v[72:75]
	v_mfma_f32_16x16x32_bf16 v[124:127], v[140:143], v[176:179], v[124:127]
	v_mfma_f32_16x16x32_bf16 v[120:123], v[154:157], v[176:179], v[120:123]
	v_mfma_f32_16x16x32_bf16 v[108:111], v[140:143], v[184:187], v[108:111]
	v_mfma_f32_16x16x32_bf16 v[104:107], v[154:157], v[184:187], v[104:107]
	v_mfma_f32_16x16x32_bf16 v[92:95], v[140:143], v[192:195], v[92:95]
	v_mfma_f32_16x16x32_bf16 v[88:91], v[154:157], v[192:195], v[88:91]
	v_mfma_f32_16x16x32_bf16 v[76:79], v[140:143], v[212:215], v[76:79]
	v_mfma_f32_16x16x32_bf16 v[72:75], v[154:157], v[212:215], v[72:75]
	s_setprio 0
	s_barrier
	s_add_i32 s46, 0, 0x14000
	v_add_u32_e32 v144, s46, v147
	s_add_i32 s44, s44, s29
	ds_read_b128 v[216:219], v144
	ds_read_b128 v[220:223], v144 offset:1024
	ds_read_b128 v[224:227], v144 offset:2048
	ds_read_b128 v[228:231], v144 offset:3072
	v_lshl_add_u64 v[144:145], s[22:23], 0, v[128:129]
	s_mov_b32 m0, s44
	v_lshl_add_u64 v[232:233], s[22:23], 0, v[130:131]
	global_load_lds_dwordx4 v[144:145], off
	s_add_i32 m0, s44, 0x2000
	s_nop 0
	global_load_lds_dwordx4 v[232:233], off
	s_barrier
	s_waitcnt lgkmcnt(0)
	s_setprio 1
	s_waitcnt lgkmcnt(0)
	v_mfma_f32_16x16x32_bf16 v[116:119], v[216:219], v[158:161], v[116:119]
	v_mfma_f32_16x16x32_bf16 v[112:115], v[224:227], v[158:161], v[112:115]
	v_mfma_f32_16x16x32_bf16 v[100:103], v[216:219], v[180:183], v[100:103]
	v_mfma_f32_16x16x32_bf16 v[96:99], v[224:227], v[180:183], v[96:99]
	v_mfma_f32_16x16x32_bf16 v[84:87], v[216:219], v[188:191], v[84:87]
	v_mfma_f32_16x16x32_bf16 v[80:83], v[224:227], v[188:191], v[80:83]
	v_mfma_f32_16x16x32_bf16 v[68:71], v[216:219], v[208:211], v[68:71]
	v_mfma_f32_16x16x32_bf16 v[64:67], v[224:227], v[208:211], v[64:67]
	v_mfma_f32_16x16x32_bf16 v[116:119], v[220:223], v[176:179], v[116:119]
	v_mfma_f32_16x16x32_bf16 v[112:115], v[228:231], v[176:179], v[112:115]
	v_mfma_f32_16x16x32_bf16 v[100:103], v[220:223], v[184:187], v[100:103]
	v_mfma_f32_16x16x32_bf16 v[96:99], v[228:231], v[184:187], v[96:99]
	v_mfma_f32_16x16x32_bf16 v[84:87], v[220:223], v[192:195], v[84:87]
	v_mfma_f32_16x16x32_bf16 v[80:83], v[228:231], v[192:195], v[80:83]
	v_mfma_f32_16x16x32_bf16 v[68:71], v[220:223], v[212:215], v[68:71]
	v_mfma_f32_16x16x32_bf16 v[64:67], v[228:231], v[212:215], v[64:67]
	s_setprio 0
	s_mov_b32 m0, s19
	v_lshl_add_u64 v[234:235], s[24:25], 0, v[128:129]
	s_barrier
	ds_read_b128 v[158:161], v149 offset:16384
	ds_read_b128 v[176:179], v149 offset:17408
	ds_read_b128 v[180:183], v149 offset:18432
	ds_read_b128 v[184:187], v149 offset:19456
	ds_read_b128 v[188:191], v149 offset:20480
	ds_read_b128 v[192:195], v149 offset:21504
	ds_read_b128 v[208:211], v149 offset:22528
	ds_read_b128 v[212:215], v149 offset:23552
	global_load_lds_dwordx4 v[234:235], off
	v_lshl_add_u64 v[236:237], s[24:25], 0, v[130:131]
	s_mov_b32 m0, s30
	s_nop 0
	global_load_lds_dwordx4 v[236:237], off
	s_barrier
	s_waitcnt lgkmcnt(0)
	s_setprio 1
	s_waitcnt lgkmcnt(0)
	v_mfma_f32_16x16x32_bf16 v[60:63], v[136:139], v[158:161], v[60:63]
	v_mfma_f32_16x16x32_bf16 v[56:59], v[150:153], v[158:161], v[56:59]
	v_mfma_f32_16x16x32_bf16 v[44:47], v[136:139], v[180:183], v[44:47]
	v_mfma_f32_16x16x32_bf16 v[40:43], v[150:153], v[180:183], v[40:43]
	v_mfma_f32_16x16x32_bf16 v[28:31], v[136:139], v[188:191], v[28:31]
	v_mfma_f32_16x16x32_bf16 v[24:27], v[150:153], v[188:191], v[24:27]
	v_mfma_f32_16x16x32_bf16 v[12:15], v[136:139], v[208:211], v[12:15]
	v_mfma_f32_16x16x32_bf16 v[8:11], v[150:153], v[208:211], v[8:11]
	v_mfma_f32_16x16x32_bf16 v[60:63], v[140:143], v[176:179], v[60:63]
	v_mfma_f32_16x16x32_bf16 v[56:59], v[154:157], v[176:179], v[56:59]
	v_mfma_f32_16x16x32_bf16 v[44:47], v[140:143], v[184:187], v[44:47]
	v_mfma_f32_16x16x32_bf16 v[40:43], v[154:157], v[184:187], v[40:43]
	v_mfma_f32_16x16x32_bf16 v[28:31], v[140:143], v[192:195], v[28:31]
	v_mfma_f32_16x16x32_bf16 v[24:27], v[154:157], v[192:195], v[24:27]
	v_mfma_f32_16x16x32_bf16 v[12:15], v[140:143], v[212:215], v[12:15]
	v_mfma_f32_16x16x32_bf16 v[8:11], v[154:157], v[212:215], v[8:11]
	s_setprio 0
	s_barrier
	s_add_u32 s44, s22, 0x80000
	s_addc_u32 s45, s23, 0
	s_add_i32 s46, s46, s29
	v_lshl_add_u64 v[136:137], s[44:45], 0, v[128:129]
	s_mov_b32 m0, s46
	s_nop 0
	global_load_lds_dwordx4 v[136:137], off
	v_lshl_add_u64 v[136:137], s[44:45], 0, v[130:131]
	s_add_i32 m0, s46, 0x2000
	s_nop 0
	global_load_lds_dwordx4 v[136:137], off
	s_waitcnt vmcnt(6)
	s_barrier
	s_setprio 1
	v_mfma_f32_16x16x32_bf16 v[52:55], v[216:219], v[158:161], v[52:55]
	v_mfma_f32_16x16x32_bf16 v[48:51], v[224:227], v[158:161], v[48:51]
	v_mfma_f32_16x16x32_bf16 v[36:39], v[216:219], v[180:183], v[36:39]
	v_mfma_f32_16x16x32_bf16 v[32:35], v[224:227], v[180:183], v[32:35]
	v_mfma_f32_16x16x32_bf16 v[20:23], v[216:219], v[188:191], v[20:23]
	v_mfma_f32_16x16x32_bf16 v[16:19], v[224:227], v[188:191], v[16:19]
	v_mfma_f32_16x16x32_bf16 v[4:7], v[216:219], v[208:211], v[4:7]
	v_mfma_f32_16x16x32_bf16 v[0:3], v[224:227], v[208:211], v[0:3]
	v_mfma_f32_16x16x32_bf16 v[52:55], v[220:223], v[176:179], v[52:55]
	v_mfma_f32_16x16x32_bf16 v[48:51], v[228:231], v[176:179], v[48:51]
	v_mfma_f32_16x16x32_bf16 v[36:39], v[220:223], v[184:187], v[36:39]
	v_mfma_f32_16x16x32_bf16 v[32:35], v[228:231], v[184:187], v[32:35]
	v_mfma_f32_16x16x32_bf16 v[20:23], v[220:223], v[192:195], v[20:23]
	v_mfma_f32_16x16x32_bf16 v[16:19], v[228:231], v[192:195], v[16:19]
	v_mfma_f32_16x16x32_bf16 v[4:7], v[220:223], v[212:215], v[4:7]
	v_mfma_f32_16x16x32_bf16 v[0:3], v[228:231], v[212:215], v[0:3]
	s_setprio 0
	s_add_i32 s44, 0, 0x18000
	v_add_u32_e32 v154, s44, v147
	s_barrier
	ds_read_b128 v[136:139], v154
	ds_read_b128 v[140:143], v154 offset:1024
	ds_read_b128 v[150:153], v154 offset:2048
	ds_read_b128 v[154:157], v154 offset:3072
	s_add_u32 s24, s24, 0x80000
	s_addc_u32 s25, s25, 0
	s_mov_b32 m0, s31
	v_lshl_add_u64 v[216:217], s[24:25], 0, v[128:129]
	ds_read_b128 v[158:161], v149 offset:32768
	ds_read_b128 v[176:179], v149 offset:33792
	ds_read_b128 v[180:183], v149 offset:34816
	ds_read_b128 v[184:187], v149 offset:35840
	ds_read_b128 v[188:191], v149 offset:36864
	ds_read_b128 v[192:195], v149 offset:37888
	ds_read_b128 v[208:211], v149 offset:38912
	ds_read_b128 v[212:215], v149 offset:39936
	global_load_lds_dwordx4 v[216:217], off
	v_lshl_add_u64 v[216:217], s[24:25], 0, v[130:131]
	s_mov_b32 m0, s34
	s_nop 0
	global_load_lds_dwordx4 v[216:217], off
	s_waitcnt lgkmcnt(8)
	s_barrier
	s_waitcnt lgkmcnt(0)
	s_setprio 1
	s_waitcnt lgkmcnt(0)
	v_mfma_f32_16x16x32_bf16 v[124:127], v[136:139], v[158:161], v[124:127]
	v_mfma_f32_16x16x32_bf16 v[120:123], v[150:153], v[158:161], v[120:123]
	v_mfma_f32_16x16x32_bf16 v[108:111], v[136:139], v[180:183], v[108:111]
	v_mfma_f32_16x16x32_bf16 v[104:107], v[150:153], v[180:183], v[104:107]
	v_mfma_f32_16x16x32_bf16 v[92:95], v[136:139], v[188:191], v[92:95]
	v_mfma_f32_16x16x32_bf16 v[88:91], v[150:153], v[188:191], v[88:91]
	v_mfma_f32_16x16x32_bf16 v[76:79], v[136:139], v[208:211], v[76:79]
	v_mfma_f32_16x16x32_bf16 v[72:75], v[150:153], v[208:211], v[72:75]
	v_mfma_f32_16x16x32_bf16 v[124:127], v[140:143], v[176:179], v[124:127]
	v_mfma_f32_16x16x32_bf16 v[120:123], v[154:157], v[176:179], v[120:123]
	v_mfma_f32_16x16x32_bf16 v[108:111], v[140:143], v[184:187], v[108:111]
	v_mfma_f32_16x16x32_bf16 v[104:107], v[154:157], v[184:187], v[104:107]
	v_mfma_f32_16x16x32_bf16 v[92:95], v[140:143], v[192:195], v[92:95]
	v_mfma_f32_16x16x32_bf16 v[88:91], v[154:157], v[192:195], v[88:91]
	v_mfma_f32_16x16x32_bf16 v[76:79], v[140:143], v[212:215], v[76:79]
	v_mfma_f32_16x16x32_bf16 v[72:75], v[154:157], v[212:215], v[72:75]
	s_setprio 0
	s_barrier
	s_add_i32 s24, 0, 0x1c000
	s_add_i32 s25, s44, s29
	v_add_u32_e32 v196, s24, v147
	v_lshl_add_u64 v[144:145], v[144:145], 0, s[6:7]
	s_mov_b32 m0, s25
	ds_read_b128 v[216:219], v196
	ds_read_b128 v[220:223], v196 offset:1024
	ds_read_b128 v[224:227], v196 offset:2048
	ds_read_b128 v[228:231], v196 offset:3072
	global_load_lds_dwordx4 v[144:145], off
	v_lshl_add_u64 v[144:145], v[232:233], 0, s[6:7]
	s_add_i32 m0, s25, 0x2000
	s_nop 0
	global_load_lds_dwordx4 v[144:145], off
	s_barrier
	s_waitcnt lgkmcnt(0)
	s_setprio 1
	s_waitcnt lgkmcnt(0)
	v_mfma_f32_16x16x32_bf16 v[116:119], v[216:219], v[158:161], v[116:119]
	v_mfma_f32_16x16x32_bf16 v[112:115], v[224:227], v[158:161], v[112:115]
	v_mfma_f32_16x16x32_bf16 v[100:103], v[216:219], v[180:183], v[100:103]
	v_mfma_f32_16x16x32_bf16 v[96:99], v[224:227], v[180:183], v[96:99]
	v_mfma_f32_16x16x32_bf16 v[84:87], v[216:219], v[188:191], v[84:87]
	v_mfma_f32_16x16x32_bf16 v[80:83], v[224:227], v[188:191], v[80:83]
	v_mfma_f32_16x16x32_bf16 v[68:71], v[216:219], v[208:211], v[68:71]
	v_mfma_f32_16x16x32_bf16 v[64:67], v[224:227], v[208:211], v[64:67]
	v_mfma_f32_16x16x32_bf16 v[116:119], v[220:223], v[176:179], v[116:119]
	v_mfma_f32_16x16x32_bf16 v[112:115], v[228:231], v[176:179], v[112:115]
	v_mfma_f32_16x16x32_bf16 v[100:103], v[220:223], v[184:187], v[100:103]
	v_mfma_f32_16x16x32_bf16 v[96:99], v[228:231], v[184:187], v[96:99]
	v_mfma_f32_16x16x32_bf16 v[84:87], v[220:223], v[192:195], v[84:87]
	v_mfma_f32_16x16x32_bf16 v[80:83], v[228:231], v[192:195], v[80:83]
	v_mfma_f32_16x16x32_bf16 v[68:71], v[220:223], v[212:215], v[68:71]
	v_mfma_f32_16x16x32_bf16 v[64:67], v[228:231], v[212:215], v[64:67]
	s_setprio 0
	s_mov_b32 m0, s35
	v_lshl_add_u64 v[144:145], v[234:235], 0, s[6:7]
	s_barrier
	ds_read_b128 v[158:161], v149 offset:49152
	ds_read_b128 v[176:179], v149 offset:50176
	ds_read_b128 v[180:183], v149 offset:51200
	ds_read_b128 v[184:187], v149 offset:52224
	ds_read_b128 v[188:191], v149 offset:53248
	ds_read_b128 v[192:195], v149 offset:54272
	ds_read_b128 v[208:211], v149 offset:55296
	ds_read_b128 v[212:215], v149 offset:56320
	global_load_lds_dwordx4 v[144:145], off
	v_lshl_add_u64 v[144:145], v[236:237], 0, s[6:7]
	s_mov_b32 m0, s36
	s_nop 0
	global_load_lds_dwordx4 v[144:145], off
	s_barrier
	s_waitcnt lgkmcnt(0)
	s_setprio 1
	s_waitcnt lgkmcnt(0)
	v_mfma_f32_16x16x32_bf16 v[60:63], v[136:139], v[158:161], v[60:63]
	v_mfma_f32_16x16x32_bf16 v[56:59], v[150:153], v[158:161], v[56:59]
	v_mfma_f32_16x16x32_bf16 v[44:47], v[136:139], v[180:183], v[44:47]
	v_mfma_f32_16x16x32_bf16 v[40:43], v[150:153], v[180:183], v[40:43]
	v_mfma_f32_16x16x32_bf16 v[28:31], v[136:139], v[188:191], v[28:31]
	v_mfma_f32_16x16x32_bf16 v[24:27], v[150:153], v[188:191], v[24:27]
	v_mfma_f32_16x16x32_bf16 v[12:15], v[136:139], v[208:211], v[12:15]
	v_mfma_f32_16x16x32_bf16 v[8:11], v[150:153], v[208:211], v[8:11]
	v_mfma_f32_16x16x32_bf16 v[60:63], v[140:143], v[176:179], v[60:63]
	v_mfma_f32_16x16x32_bf16 v[56:59], v[154:157], v[176:179], v[56:59]
	v_mfma_f32_16x16x32_bf16 v[44:47], v[140:143], v[184:187], v[44:47]
	v_mfma_f32_16x16x32_bf16 v[40:43], v[154:157], v[184:187], v[40:43]
	v_mfma_f32_16x16x32_bf16 v[28:31], v[140:143], v[192:195], v[28:31]
	v_mfma_f32_16x16x32_bf16 v[24:27], v[154:157], v[192:195], v[24:27]
	v_mfma_f32_16x16x32_bf16 v[12:15], v[140:143], v[212:215], v[12:15]
	v_mfma_f32_16x16x32_bf16 v[8:11], v[154:157], v[212:215], v[8:11]
	s_setprio 0
	s_barrier
	s_add_u32 s22, s22, 0x80080
	s_addc_u32 s23, s23, 0
	s_add_i32 s24, s24, s29
	v_lshl_add_u64 v[136:137], s[22:23], 0, v[128:129]
	s_mov_b32 m0, s24
	s_nop 0
	global_load_lds_dwordx4 v[136:137], off
	v_lshl_add_u64 v[136:137], s[22:23], 0, v[130:131]
	s_add_i32 m0, s24, 0x2000
	s_nop 0
	global_load_lds_dwordx4 v[136:137], off
	s_waitcnt vmcnt(6)
	s_barrier
	s_setprio 1
	v_mfma_f32_16x16x32_bf16 v[52:55], v[216:219], v[158:161], v[52:55]
	v_mfma_f32_16x16x32_bf16 v[48:51], v[224:227], v[158:161], v[48:51]
	v_mfma_f32_16x16x32_bf16 v[36:39], v[216:219], v[180:183], v[36:39]
	v_mfma_f32_16x16x32_bf16 v[32:35], v[224:227], v[180:183], v[32:35]
	v_mfma_f32_16x16x32_bf16 v[20:23], v[216:219], v[188:191], v[20:23]
	v_mfma_f32_16x16x32_bf16 v[16:19], v[224:227], v[188:191], v[16:19]
	v_mfma_f32_16x16x32_bf16 v[4:7], v[216:219], v[208:211], v[4:7]
	v_mfma_f32_16x16x32_bf16 v[0:3], v[224:227], v[208:211], v[0:3]
	v_mfma_f32_16x16x32_bf16 v[52:55], v[220:223], v[176:179], v[52:55]
	v_mfma_f32_16x16x32_bf16 v[48:51], v[228:231], v[176:179], v[48:51]
	v_mfma_f32_16x16x32_bf16 v[36:39], v[220:223], v[184:187], v[36:39]
	v_mfma_f32_16x16x32_bf16 v[32:35], v[228:231], v[184:187], v[32:35]
	v_mfma_f32_16x16x32_bf16 v[20:23], v[220:223], v[192:195], v[20:23]
	v_mfma_f32_16x16x32_bf16 v[16:19], v[228:231], v[192:195], v[16:19]
	v_mfma_f32_16x16x32_bf16 v[4:7], v[220:223], v[212:215], v[4:7]
	v_mfma_f32_16x16x32_bf16 v[0:3], v[228:231], v[212:215], v[0:3]
	s_setprio 0
	s_add_i32 s43, s43, 2
	s_add_u32 s20, s20, 0x100
	s_addc_u32 s21, s21, 0
	s_add_u32 s41, s41, 0x100
	s_addc_u32 s42, s42, 0
	s_cmp_gt_u32 s43, 29
	s_barrier
	s_cbranch_scc0 .LBB0_102
	v_lshl_add_u32 v136, s18, 8, v146
	v_lshl_or_b32 v137, s38, 8, v148
	v_readlane_b32 s22, v255, 34
	v_readlane_b32 s23, v255, 35
	v_lshl_add_u32 v137, v136, 11, v137
	v_lshlrev_b32_e32 v138, 1, v137
	v_lshlrev_b32_e32 v139, 2, v137
	s_mov_b32 s38, s10
	s_mov_b32 s18, s12
	v_mov_b32_e32 v142, v139
	v_mov_b32_e32 v194, v138
	global_load_dwordx2 v[154:155], v194, s[22:23] offset:0
	global_load_dwordx4 v[150:153], v142, s[48:49] offset:0
	global_load_dwordx2 v[160:161], v194, s[22:23] offset:32
	global_load_dwordx4 v[156:159], v142, s[48:49] offset:64
	global_load_dwordx2 v[180:181], v194, s[22:23] offset:256
	global_load_dwordx4 v[176:179], v142, s[48:49] offset:512
	global_load_dwordx2 v[186:187], v194, s[22:23] offset:288
	global_load_dwordx4 v[182:185], v142, s[48:49] offset:576
	v_add_u32_e32 v143, 0x20000, v139
	v_add_u32_e32 v194, 0x10000, v138
	global_load_dwordx2 v[192:193], v194, s[22:23] offset:0
	global_load_dwordx4 v[188:191], v143, s[48:49] offset:0
	global_load_dwordx2 v[212:213], v194, s[22:23] offset:32
	global_load_dwordx4 v[208:211], v143, s[48:49] offset:64
	global_load_dwordx2 v[218:219], v194, s[22:23] offset:256
	global_load_dwordx4 v[214:217], v143, s[48:49] offset:512
	global_load_dwordx2 v[224:225], v194, s[22:23] offset:288
	global_load_dwordx4 v[220:223], v143, s[48:49] offset:576
	v_add_u32_e32 v144, 0x40000, v139
	v_add_u32_e32 v194, 0x20000, v138
	global_load_dwordx2 v[230:231], v194, s[22:23] offset:0
	global_load_dwordx4 v[226:229], v144, s[48:49] offset:0
	global_load_dwordx2 v[236:237], v194, s[22:23] offset:32
	global_load_dwordx4 v[232:235], v144, s[48:49] offset:64
	v_mul_f32_e32 v124, 0xbfb8aa3b, v124
	v_mul_f32_e32 v125, 0xbfb8aa3b, v125
	v_mul_f32_e32 v126, 0xbfb8aa3b, v126
	v_mul_f32_e32 v127, 0xbfb8aa3b, v127
	v_exp_f32_e32 v124, v124
	v_exp_f32_e32 v125, v125
	v_exp_f32_e32 v126, v126
	v_exp_f32_e32 v127, v127
	v_add_f32_e32 v124, 1.0, v124
	v_add_f32_e32 v125, 1.0, v125
	v_add_f32_e32 v126, 1.0, v126
	v_add_f32_e32 v127, 1.0, v127
	v_rcp_f32_e32 v124, v124
	v_rcp_f32_e32 v125, v125
	v_rcp_f32_e32 v126, v126
	v_rcp_f32_e32 v127, v127
	s_waitcnt vmcnt(18)
	v_lshlrev_b32_e32 v140, 16, v154
	v_and_b32_e32 v141, 0xffff0000, v154
	v_lshlrev_b32_e32 v154, 16, v155
	v_and_b32_e32 v155, 0xffff0000, v155
	v_pk_mul_f32 v[140:141], v[140:141], s[74:75] op_sel_hi:[1,0]
	v_pk_mul_f32 v[154:155], v[154:155], s[74:75] op_sel_hi:[1,0]
	v_pk_fma_f32 v[124:125], v[124:125], v[150:151], v[140:141]
	v_pk_fma_f32 v[126:127], v[126:127], v[152:153], v[154:155]
	global_store_dwordx4 v142, v[124:127], s[76:77] offset:0
	global_load_dwordx2 v[154:155], v194, s[22:23] offset:256
	global_load_dwordx4 v[150:153], v144, s[48:49] offset:512
	v_mul_f32_e32 v120, 0xbfb8aa3b, v120
	v_mul_f32_e32 v121, 0xbfb8aa3b, v121
	v_mul_f32_e32 v122, 0xbfb8aa3b, v122
	v_mul_f32_e32 v123, 0xbfb8aa3b, v123
	v_exp_f32_e32 v120, v120
	v_exp_f32_e32 v121, v121
	v_exp_f32_e32 v122, v122
	v_exp_f32_e32 v123, v123
	v_add_f32_e32 v120, 1.0, v120
	v_add_f32_e32 v121, 1.0, v121
	v_add_f32_e32 v122, 1.0, v122
	v_add_f32_e32 v123, 1.0, v123
	v_rcp_f32_e32 v120, v120
	v_rcp_f32_e32 v121, v121
	v_rcp_f32_e32 v122, v122
	v_rcp_f32_e32 v123, v123
	s_waitcnt vmcnt(19)
	v_lshlrev_b32_e32 v140, 16, v160
	v_and_b32_e32 v141, 0xffff0000, v160
	v_lshlrev_b32_e32 v160, 16, v161
	v_and_b32_e32 v161, 0xffff0000, v161
	v_pk_mul_f32 v[140:141], v[140:141], s[74:75] op_sel_hi:[1,0]
	v_pk_mul_f32 v[160:161], v[160:161], s[74:75] op_sel_hi:[1,0]
	v_pk_fma_f32 v[120:121], v[120:121], v[156:157], v[140:141]
	v_pk_fma_f32 v[122:123], v[122:123], v[158:159], v[160:161]
	global_store_dwordx4 v142, v[120:123], s[76:77] offset:64
	global_load_dwordx2 v[160:161], v194, s[22:23] offset:288
	global_load_dwordx4 v[156:159], v144, s[48:49] offset:576
	v_mul_f32_e32 v116, 0xbfb8aa3b, v116
	v_mul_f32_e32 v117, 0xbfb8aa3b, v117
	v_mul_f32_e32 v118, 0xbfb8aa3b, v118
	v_mul_f32_e32 v119, 0xbfb8aa3b, v119
	v_exp_f32_e32 v116, v116
	v_exp_f32_e32 v117, v117
	v_exp_f32_e32 v118, v118
	v_exp_f32_e32 v119, v119
	v_add_f32_e32 v116, 1.0, v116
	v_add_f32_e32 v117, 1.0, v117
	v_add_f32_e32 v118, 1.0, v118
	v_add_f32_e32 v119, 1.0, v119
	v_rcp_f32_e32 v116, v116
	v_rcp_f32_e32 v117, v117
	v_rcp_f32_e32 v118, v118
	v_rcp_f32_e32 v119, v119
	s_waitcnt vmcnt(20)
	v_lshlrev_b32_e32 v140, 16, v180
	v_and_b32_e32 v141, 0xffff0000, v180
	v_lshlrev_b32_e32 v180, 16, v181
	v_and_b32_e32 v181, 0xffff0000, v181
	v_pk_mul_f32 v[140:141], v[140:141], s[74:75] op_sel_hi:[1,0]
	v_pk_mul_f32 v[180:181], v[180:181], s[74:75] op_sel_hi:[1,0]
	v_pk_fma_f32 v[116:117], v[116:117], v[176:177], v[140:141]
	v_pk_fma_f32 v[118:119], v[118:119], v[178:179], v[180:181]
	global_store_dwordx4 v142, v[116:119], s[76:77] offset:512
	v_add_u32_e32 v145, 0x60000, v139
	v_add_u32_e32 v194, 0x30000, v138
	global_load_dwordx2 v[180:181], v194, s[22:23] offset:0
	global_load_dwordx4 v[176:179], v145, s[48:49] offset:0
	v_mul_f32_e32 v112, 0xbfb8aa3b, v112
	v_mul_f32_e32 v113, 0xbfb8aa3b, v113
	v_mul_f32_e32 v114, 0xbfb8aa3b, v114
	v_mul_f32_e32 v115, 0xbfb8aa3b, v115
	v_exp_f32_e32 v112, v112
	v_exp_f32_e32 v113, v113
	v_exp_f32_e32 v114, v114
	v_exp_f32_e32 v115, v115
	v_add_f32_e32 v112, 1.0, v112
	v_add_f32_e32 v113, 1.0, v113
	v_add_f32_e32 v114, 1.0, v114
	v_add_f32_e32 v115, 1.0, v115
	v_rcp_f32_e32 v112, v112
	v_rcp_f32_e32 v113, v113
	v_rcp_f32_e32 v114, v114
	v_rcp_f32_e32 v115, v115
	s_waitcnt vmcnt(21)
	v_lshlrev_b32_e32 v140, 16, v186
	v_and_b32_e32 v141, 0xffff0000, v186
	v_lshlrev_b32_e32 v186, 16, v187
	v_and_b32_e32 v187, 0xffff0000, v187
	v_pk_mul_f32 v[140:141], v[140:141], s[74:75] op_sel_hi:[1,0]
	v_pk_mul_f32 v[186:187], v[186:187], s[74:75] op_sel_hi:[1,0]
	v_pk_fma_f32 v[112:113], v[112:113], v[182:183], v[140:141]
	v_pk_fma_f32 v[114:115], v[114:115], v[184:185], v[186:187]
	global_store_dwordx4 v142, v[112:115], s[76:77] offset:576
	global_load_dwordx2 v[186:187], v194, s[22:23] offset:32
	global_load_dwordx4 v[182:185], v145, s[48:49] offset:64
	v_mul_f32_e32 v108, 0xbfb8aa3b, v108
	v_mul_f32_e32 v109, 0xbfb8aa3b, v109
	v_mul_f32_e32 v110, 0xbfb8aa3b, v110
	v_mul_f32_e32 v111, 0xbfb8aa3b, v111
	v_exp_f32_e32 v108, v108
	v_exp_f32_e32 v109, v109
	v_exp_f32_e32 v110, v110
	v_exp_f32_e32 v111, v111
	v_add_f32_e32 v108, 1.0, v108
	v_add_f32_e32 v109, 1.0, v109
	v_add_f32_e32 v110, 1.0, v110
	v_add_f32_e32 v111, 1.0, v111
	v_rcp_f32_e32 v108, v108
	v_rcp_f32_e32 v109, v109
	v_rcp_f32_e32 v110, v110
	v_rcp_f32_e32 v111, v111
	s_waitcnt vmcnt(22)
	v_lshlrev_b32_e32 v140, 16, v192
	v_and_b32_e32 v141, 0xffff0000, v192
	v_lshlrev_b32_e32 v192, 16, v193
	v_and_b32_e32 v193, 0xffff0000, v193
	v_pk_mul_f32 v[140:141], v[140:141], s[74:75] op_sel_hi:[1,0]
	v_pk_mul_f32 v[192:193], v[192:193], s[74:75] op_sel_hi:[1,0]
	v_pk_fma_f32 v[108:109], v[108:109], v[188:189], v[140:141]
	v_pk_fma_f32 v[110:111], v[110:111], v[190:191], v[192:193]
	global_store_dwordx4 v143, v[108:111], s[76:77] offset:0
	global_load_dwordx2 v[192:193], v194, s[22:23] offset:256
	global_load_dwordx4 v[188:191], v145, s[48:49] offset:512
	v_mul_f32_e32 v104, 0xbfb8aa3b, v104
	v_mul_f32_e32 v105, 0xbfb8aa3b, v105
	v_mul_f32_e32 v106, 0xbfb8aa3b, v106
	v_mul_f32_e32 v107, 0xbfb8aa3b, v107
	v_exp_f32_e32 v104, v104
	v_exp_f32_e32 v105, v105
	v_exp_f32_e32 v106, v106
	v_exp_f32_e32 v107, v107
	v_add_f32_e32 v104, 1.0, v104
	v_add_f32_e32 v105, 1.0, v105
	v_add_f32_e32 v106, 1.0, v106
	v_add_f32_e32 v107, 1.0, v107
	v_rcp_f32_e32 v104, v104
	v_rcp_f32_e32 v105, v105
	v_rcp_f32_e32 v106, v106
	v_rcp_f32_e32 v107, v107
	s_waitcnt vmcnt(23)
	v_lshlrev_b32_e32 v140, 16, v212
	v_and_b32_e32 v141, 0xffff0000, v212
	v_lshlrev_b32_e32 v212, 16, v213
	v_and_b32_e32 v213, 0xffff0000, v213
	v_pk_mul_f32 v[140:141], v[140:141], s[74:75] op_sel_hi:[1,0]
	v_pk_mul_f32 v[212:213], v[212:213], s[74:75] op_sel_hi:[1,0]
	v_pk_fma_f32 v[104:105], v[104:105], v[208:209], v[140:141]
	v_pk_fma_f32 v[106:107], v[106:107], v[210:211], v[212:213]
	global_store_dwordx4 v143, v[104:107], s[76:77] offset:64
	global_load_dwordx2 v[212:213], v194, s[22:23] offset:288
	global_load_dwordx4 v[208:211], v145, s[48:49] offset:576
	v_mul_f32_e32 v100, 0xbfb8aa3b, v100
	v_mul_f32_e32 v101, 0xbfb8aa3b, v101
	v_mul_f32_e32 v102, 0xbfb8aa3b, v102
	v_mul_f32_e32 v103, 0xbfb8aa3b, v103
	v_exp_f32_e32 v100, v100
	v_exp_f32_e32 v101, v101
	v_exp_f32_e32 v102, v102
	v_exp_f32_e32 v103, v103
	v_add_f32_e32 v100, 1.0, v100
	v_add_f32_e32 v101, 1.0, v101
	v_add_f32_e32 v102, 1.0, v102
	v_add_f32_e32 v103, 1.0, v103
	v_rcp_f32_e32 v100, v100
	v_rcp_f32_e32 v101, v101
	v_rcp_f32_e32 v102, v102
	v_rcp_f32_e32 v103, v103
	s_waitcnt vmcnt(24)
	v_lshlrev_b32_e32 v140, 16, v218
	v_and_b32_e32 v141, 0xffff0000, v218
	v_lshlrev_b32_e32 v218, 16, v219
	v_and_b32_e32 v219, 0xffff0000, v219
	v_pk_mul_f32 v[140:141], v[140:141], s[74:75] op_sel_hi:[1,0]
	v_pk_mul_f32 v[218:219], v[218:219], s[74:75] op_sel_hi:[1,0]
	v_pk_fma_f32 v[100:101], v[100:101], v[214:215], v[140:141]
	v_pk_fma_f32 v[102:103], v[102:103], v[216:217], v[218:219]
	global_store_dwordx4 v143, v[100:103], s[76:77] offset:512
	v_add_u32_e32 v142, 0x100000, v139
	v_add_u32_e32 v194, 0x80000, v138
	global_load_dwordx2 v[218:219], v194, s[22:23] offset:0
	global_load_dwordx4 v[214:217], v142, s[48:49] offset:0
	v_mul_f32_e32 v96, 0xbfb8aa3b, v96
	v_mul_f32_e32 v97, 0xbfb8aa3b, v97
	v_mul_f32_e32 v98, 0xbfb8aa3b, v98
	v_mul_f32_e32 v99, 0xbfb8aa3b, v99
	v_exp_f32_e32 v96, v96
	v_exp_f32_e32 v97, v97
	v_exp_f32_e32 v98, v98
	v_exp_f32_e32 v99, v99
	v_add_f32_e32 v96, 1.0, v96
	v_add_f32_e32 v97, 1.0, v97
	v_add_f32_e32 v98, 1.0, v98
	v_add_f32_e32 v99, 1.0, v99
	v_rcp_f32_e32 v96, v96
	v_rcp_f32_e32 v97, v97
	v_rcp_f32_e32 v98, v98
	v_rcp_f32_e32 v99, v99
	s_waitcnt vmcnt(25)
	v_lshlrev_b32_e32 v140, 16, v224
	v_and_b32_e32 v141, 0xffff0000, v224
	v_lshlrev_b32_e32 v224, 16, v225
	v_and_b32_e32 v225, 0xffff0000, v225
	v_pk_mul_f32 v[140:141], v[140:141], s[74:75] op_sel_hi:[1,0]
	v_pk_mul_f32 v[224:225], v[224:225], s[74:75] op_sel_hi:[1,0]
	v_pk_fma_f32 v[96:97], v[96:97], v[220:221], v[140:141]
	v_pk_fma_f32 v[98:99], v[98:99], v[222:223], v[224:225]
	global_store_dwordx4 v143, v[96:99], s[76:77] offset:576
	global_load_dwordx2 v[224:225], v194, s[22:23] offset:32
	global_load_dwordx4 v[220:223], v142, s[48:49] offset:64
	v_mul_f32_e32 v92, 0xbfb8aa3b, v92
	v_mul_f32_e32 v93, 0xbfb8aa3b, v93
	v_mul_f32_e32 v94, 0xbfb8aa3b, v94
	v_mul_f32_e32 v95, 0xbfb8aa3b, v95
	v_exp_f32_e32 v92, v92
	v_exp_f32_e32 v93, v93
	v_exp_f32_e32 v94, v94
	v_exp_f32_e32 v95, v95
	v_add_f32_e32 v92, 1.0, v92
	v_add_f32_e32 v93, 1.0, v93
	v_add_f32_e32 v94, 1.0, v94
	v_add_f32_e32 v95, 1.0, v95
	v_rcp_f32_e32 v92, v92
	v_rcp_f32_e32 v93, v93
	v_rcp_f32_e32 v94, v94
	v_rcp_f32_e32 v95, v95
	s_waitcnt vmcnt(26)
	v_lshlrev_b32_e32 v140, 16, v230
	v_and_b32_e32 v141, 0xffff0000, v230
	v_lshlrev_b32_e32 v230, 16, v231
	v_and_b32_e32 v231, 0xffff0000, v231
	v_pk_mul_f32 v[140:141], v[140:141], s[74:75] op_sel_hi:[1,0]
	v_pk_mul_f32 v[230:231], v[230:231], s[74:75] op_sel_hi:[1,0]
	v_pk_fma_f32 v[92:93], v[92:93], v[226:227], v[140:141]
	v_pk_fma_f32 v[94:95], v[94:95], v[228:229], v[230:231]
	global_store_dwordx4 v144, v[92:95], s[76:77] offset:0
	global_load_dwordx2 v[230:231], v194, s[22:23] offset:256
	global_load_dwordx4 v[226:229], v142, s[48:49] offset:512
	v_mul_f32_e32 v88, 0xbfb8aa3b, v88
	v_mul_f32_e32 v89, 0xbfb8aa3b, v89
	v_mul_f32_e32 v90, 0xbfb8aa3b, v90
	v_mul_f32_e32 v91, 0xbfb8aa3b, v91
	v_exp_f32_e32 v88, v88
	v_exp_f32_e32 v89, v89
	v_exp_f32_e32 v90, v90
	v_exp_f32_e32 v91, v91
	v_add_f32_e32 v88, 1.0, v88
	v_add_f32_e32 v89, 1.0, v89
	v_add_f32_e32 v90, 1.0, v90
	v_add_f32_e32 v91, 1.0, v91
	v_rcp_f32_e32 v88, v88
	v_rcp_f32_e32 v89, v89
	v_rcp_f32_e32 v90, v90
	v_rcp_f32_e32 v91, v91
	s_waitcnt vmcnt(27)
	v_lshlrev_b32_e32 v140, 16, v236
	v_and_b32_e32 v141, 0xffff0000, v236
	v_lshlrev_b32_e32 v236, 16, v237
	v_and_b32_e32 v237, 0xffff0000, v237
	v_pk_mul_f32 v[140:141], v[140:141], s[74:75] op_sel_hi:[1,0]
	v_pk_mul_f32 v[236:237], v[236:237], s[74:75] op_sel_hi:[1,0]
	v_pk_fma_f32 v[88:89], v[88:89], v[232:233], v[140:141]
	v_pk_fma_f32 v[90:91], v[90:91], v[234:235], v[236:237]
	global_store_dwordx4 v144, v[88:91], s[76:77] offset:64
	global_load_dwordx2 v[236:237], v194, s[22:23] offset:288
	global_load_dwordx4 v[232:235], v142, s[48:49] offset:576
	v_mul_f32_e32 v84, 0xbfb8aa3b, v84
	v_mul_f32_e32 v85, 0xbfb8aa3b, v85
	v_mul_f32_e32 v86, 0xbfb8aa3b, v86
	v_mul_f32_e32 v87, 0xbfb8aa3b, v87
	v_exp_f32_e32 v84, v84
	v_exp_f32_e32 v85, v85
	v_exp_f32_e32 v86, v86
	v_exp_f32_e32 v87, v87
	v_add_f32_e32 v84, 1.0, v84
	v_add_f32_e32 v85, 1.0, v85
	v_add_f32_e32 v86, 1.0, v86
	v_add_f32_e32 v87, 1.0, v87
	v_rcp_f32_e32 v84, v84
	v_rcp_f32_e32 v85, v85
	v_rcp_f32_e32 v86, v86
	v_rcp_f32_e32 v87, v87
	s_waitcnt vmcnt(27)
	v_lshlrev_b32_e32 v140, 16, v154
	v_and_b32_e32 v141, 0xffff0000, v154
	v_lshlrev_b32_e32 v154, 16, v155
	v_and_b32_e32 v155, 0xffff0000, v155
	v_pk_mul_f32 v[140:141], v[140:141], s[74:75] op_sel_hi:[1,0]
	v_pk_mul_f32 v[154:155], v[154:155], s[74:75] op_sel_hi:[1,0]
	v_pk_fma_f32 v[84:85], v[84:85], v[150:151], v[140:141]
	v_pk_fma_f32 v[86:87], v[86:87], v[152:153], v[154:155]
	global_store_dwordx4 v144, v[84:87], s[76:77] offset:512
	v_add_u32_e32 v143, 0x120000, v139
	v_add_u32_e32 v194, 0x90000, v138
	global_load_dwordx2 v[154:155], v194, s[22:23] offset:0
	global_load_dwordx4 v[150:153], v143, s[48:49] offset:0
	v_mul_f32_e32 v80, 0xbfb8aa3b, v80
	v_mul_f32_e32 v81, 0xbfb8aa3b, v81
	v_mul_f32_e32 v82, 0xbfb8aa3b, v82
	v_mul_f32_e32 v83, 0xbfb8aa3b, v83
	v_exp_f32_e32 v80, v80
	v_exp_f32_e32 v81, v81
	v_exp_f32_e32 v82, v82
	v_exp_f32_e32 v83, v83
	v_add_f32_e32 v80, 1.0, v80
	v_add_f32_e32 v81, 1.0, v81
	v_add_f32_e32 v82, 1.0, v82
	v_add_f32_e32 v83, 1.0, v83
	v_rcp_f32_e32 v80, v80
	v_rcp_f32_e32 v81, v81
	v_rcp_f32_e32 v82, v82
	v_rcp_f32_e32 v83, v83
	s_waitcnt vmcnt(27)
	v_lshlrev_b32_e32 v140, 16, v160
	v_and_b32_e32 v141, 0xffff0000, v160
	v_lshlrev_b32_e32 v160, 16, v161
	v_and_b32_e32 v161, 0xffff0000, v161
	v_pk_mul_f32 v[140:141], v[140:141], s[74:75] op_sel_hi:[1,0]
	v_pk_mul_f32 v[160:161], v[160:161], s[74:75] op_sel_hi:[1,0]
	v_pk_fma_f32 v[80:81], v[80:81], v[156:157], v[140:141]
	v_pk_fma_f32 v[82:83], v[82:83], v[158:159], v[160:161]
	global_store_dwordx4 v144, v[80:83], s[76:77] offset:576
	global_load_dwordx2 v[160:161], v194, s[22:23] offset:32
	global_load_dwordx4 v[156:159], v143, s[48:49] offset:64
	v_mul_f32_e32 v76, 0xbfb8aa3b, v76
	v_mul_f32_e32 v77, 0xbfb8aa3b, v77
	v_mul_f32_e32 v78, 0xbfb8aa3b, v78
	v_mul_f32_e32 v79, 0xbfb8aa3b, v79
	v_exp_f32_e32 v76, v76
	v_exp_f32_e32 v77, v77
	v_exp_f32_e32 v78, v78
	v_exp_f32_e32 v79, v79
	v_add_f32_e32 v76, 1.0, v76
	v_add_f32_e32 v77, 1.0, v77
	v_add_f32_e32 v78, 1.0, v78
	v_add_f32_e32 v79, 1.0, v79
	v_rcp_f32_e32 v76, v76
	v_rcp_f32_e32 v77, v77
	v_rcp_f32_e32 v78, v78
	v_rcp_f32_e32 v79, v79
	s_waitcnt vmcnt(27)
	v_lshlrev_b32_e32 v140, 16, v180
	v_and_b32_e32 v141, 0xffff0000, v180
	v_lshlrev_b32_e32 v180, 16, v181
	v_and_b32_e32 v181, 0xffff0000, v181
	v_pk_mul_f32 v[140:141], v[140:141], s[74:75] op_sel_hi:[1,0]
	v_pk_mul_f32 v[180:181], v[180:181], s[74:75] op_sel_hi:[1,0]
	v_pk_fma_f32 v[76:77], v[76:77], v[176:177], v[140:141]
	v_pk_fma_f32 v[78:79], v[78:79], v[178:179], v[180:181]
	global_store_dwordx4 v145, v[76:79], s[76:77] offset:0
	global_load_dwordx2 v[180:181], v194, s[22:23] offset:256
	global_load_dwordx4 v[176:179], v143, s[48:49] offset:512
	v_mul_f32_e32 v72, 0xbfb8aa3b, v72
	v_mul_f32_e32 v73, 0xbfb8aa3b, v73
	v_mul_f32_e32 v74, 0xbfb8aa3b, v74
	v_mul_f32_e32 v75, 0xbfb8aa3b, v75
	v_exp_f32_e32 v72, v72
	v_exp_f32_e32 v73, v73
	v_exp_f32_e32 v74, v74
	v_exp_f32_e32 v75, v75
	v_add_f32_e32 v72, 1.0, v72
	v_add_f32_e32 v73, 1.0, v73
	v_add_f32_e32 v74, 1.0, v74
	v_add_f32_e32 v75, 1.0, v75
	v_rcp_f32_e32 v72, v72
	v_rcp_f32_e32 v73, v73
	v_rcp_f32_e32 v74, v74
	v_rcp_f32_e32 v75, v75
	s_waitcnt vmcnt(27)
	v_lshlrev_b32_e32 v140, 16, v186
	v_and_b32_e32 v141, 0xffff0000, v186
	v_lshlrev_b32_e32 v186, 16, v187
	v_and_b32_e32 v187, 0xffff0000, v187
	v_pk_mul_f32 v[140:141], v[140:141], s[74:75] op_sel_hi:[1,0]
	v_pk_mul_f32 v[186:187], v[186:187], s[74:75] op_sel_hi:[1,0]
	v_pk_fma_f32 v[72:73], v[72:73], v[182:183], v[140:141]
	v_pk_fma_f32 v[74:75], v[74:75], v[184:185], v[186:187]
	global_store_dwordx4 v145, v[72:75], s[76:77] offset:64
	global_load_dwordx2 v[186:187], v194, s[22:23] offset:288
	global_load_dwordx4 v[182:185], v143, s[48:49] offset:576
	v_mul_f32_e32 v68, 0xbfb8aa3b, v68
	v_mul_f32_e32 v69, 0xbfb8aa3b, v69
	v_mul_f32_e32 v70, 0xbfb8aa3b, v70
	v_mul_f32_e32 v71, 0xbfb8aa3b, v71
	v_exp_f32_e32 v68, v68
	v_exp_f32_e32 v69, v69
	v_exp_f32_e32 v70, v70
	v_exp_f32_e32 v71, v71
	v_add_f32_e32 v68, 1.0, v68
	v_add_f32_e32 v69, 1.0, v69
	v_add_f32_e32 v70, 1.0, v70
	v_add_f32_e32 v71, 1.0, v71
	v_rcp_f32_e32 v68, v68
	v_rcp_f32_e32 v69, v69
	v_rcp_f32_e32 v70, v70
	v_rcp_f32_e32 v71, v71
	s_waitcnt vmcnt(27)
	v_lshlrev_b32_e32 v140, 16, v192
	v_and_b32_e32 v141, 0xffff0000, v192
	v_lshlrev_b32_e32 v192, 16, v193
	v_and_b32_e32 v193, 0xffff0000, v193
	v_pk_mul_f32 v[140:141], v[140:141], s[74:75] op_sel_hi:[1,0]
	v_pk_mul_f32 v[192:193], v[192:193], s[74:75] op_sel_hi:[1,0]
	v_pk_fma_f32 v[68:69], v[68:69], v[188:189], v[140:141]
	v_pk_fma_f32 v[70:71], v[70:71], v[190:191], v[192:193]
	global_store_dwordx4 v145, v[68:71], s[76:77] offset:512
	v_add_u32_e32 v144, 0x140000, v139
	v_add_u32_e32 v194, 0xa0000, v138
	global_load_dwordx2 v[192:193], v194, s[22:23] offset:0
	global_load_dwordx4 v[188:191], v144, s[48:49] offset:0
	v_mul_f32_e32 v64, 0xbfb8aa3b, v64
	v_mul_f32_e32 v65, 0xbfb8aa3b, v65
	v_mul_f32_e32 v66, 0xbfb8aa3b, v66
	v_mul_f32_e32 v67, 0xbfb8aa3b, v67
	v_exp_f32_e32 v64, v64
	v_exp_f32_e32 v65, v65
	v_exp_f32_e32 v66, v66
	v_exp_f32_e32 v67, v67
	v_add_f32_e32 v64, 1.0, v64
	v_add_f32_e32 v65, 1.0, v65
	v_add_f32_e32 v66, 1.0, v66
	v_add_f32_e32 v67, 1.0, v67
	v_rcp_f32_e32 v64, v64
	v_rcp_f32_e32 v65, v65
	v_rcp_f32_e32 v66, v66
	v_rcp_f32_e32 v67, v67
	s_waitcnt vmcnt(27)
	v_lshlrev_b32_e32 v140, 16, v212
	v_and_b32_e32 v141, 0xffff0000, v212
	v_lshlrev_b32_e32 v212, 16, v213
	v_and_b32_e32 v213, 0xffff0000, v213
	v_pk_mul_f32 v[140:141], v[140:141], s[74:75] op_sel_hi:[1,0]
	v_pk_mul_f32 v[212:213], v[212:213], s[74:75] op_sel_hi:[1,0]
	v_pk_fma_f32 v[64:65], v[64:65], v[208:209], v[140:141]
	v_pk_fma_f32 v[66:67], v[66:67], v[210:211], v[212:213]
	global_store_dwordx4 v145, v[64:67], s[76:77] offset:576
	global_load_dwordx2 v[212:213], v194, s[22:23] offset:32
	global_load_dwordx4 v[208:211], v144, s[48:49] offset:64
	v_mul_f32_e32 v60, 0xbfb8aa3b, v60
	v_mul_f32_e32 v61, 0xbfb8aa3b, v61
	v_mul_f32_e32 v62, 0xbfb8aa3b, v62
	v_mul_f32_e32 v63, 0xbfb8aa3b, v63
	v_exp_f32_e32 v60, v60
	v_exp_f32_e32 v61, v61
	v_exp_f32_e32 v62, v62
	v_exp_f32_e32 v63, v63
	v_add_f32_e32 v60, 1.0, v60
	v_add_f32_e32 v61, 1.0, v61
	v_add_f32_e32 v62, 1.0, v62
	v_add_f32_e32 v63, 1.0, v63
	v_rcp_f32_e32 v60, v60
	v_rcp_f32_e32 v61, v61
	v_rcp_f32_e32 v62, v62
	v_rcp_f32_e32 v63, v63
	s_waitcnt vmcnt(27)
	v_lshlrev_b32_e32 v140, 16, v218
	v_and_b32_e32 v141, 0xffff0000, v218
	v_lshlrev_b32_e32 v218, 16, v219
	v_and_b32_e32 v219, 0xffff0000, v219
	v_pk_mul_f32 v[140:141], v[140:141], s[74:75] op_sel_hi:[1,0]
	v_pk_mul_f32 v[218:219], v[218:219], s[74:75] op_sel_hi:[1,0]
	v_pk_fma_f32 v[60:61], v[60:61], v[214:215], v[140:141]
	v_pk_fma_f32 v[62:63], v[62:63], v[216:217], v[218:219]
	global_store_dwordx4 v142, v[60:63], s[76:77] offset:0
	global_load_dwordx2 v[218:219], v194, s[22:23] offset:256
	global_load_dwordx4 v[214:217], v144, s[48:49] offset:512
	v_mul_f32_e32 v56, 0xbfb8aa3b, v56
	v_mul_f32_e32 v57, 0xbfb8aa3b, v57
	v_mul_f32_e32 v58, 0xbfb8aa3b, v58
	v_mul_f32_e32 v59, 0xbfb8aa3b, v59
	v_exp_f32_e32 v56, v56
	v_exp_f32_e32 v57, v57
	v_exp_f32_e32 v58, v58
	v_exp_f32_e32 v59, v59
	v_add_f32_e32 v56, 1.0, v56
	v_add_f32_e32 v57, 1.0, v57
	v_add_f32_e32 v58, 1.0, v58
	v_add_f32_e32 v59, 1.0, v59
	v_rcp_f32_e32 v56, v56
	v_rcp_f32_e32 v57, v57
	v_rcp_f32_e32 v58, v58
	v_rcp_f32_e32 v59, v59
	s_waitcnt vmcnt(27)
	v_lshlrev_b32_e32 v140, 16, v224
	v_and_b32_e32 v141, 0xffff0000, v224
	v_lshlrev_b32_e32 v224, 16, v225
	v_and_b32_e32 v225, 0xffff0000, v225
	v_pk_mul_f32 v[140:141], v[140:141], s[74:75] op_sel_hi:[1,0]
	v_pk_mul_f32 v[224:225], v[224:225], s[74:75] op_sel_hi:[1,0]
	v_pk_fma_f32 v[56:57], v[56:57], v[220:221], v[140:141]
	v_pk_fma_f32 v[58:59], v[58:59], v[222:223], v[224:225]
	global_store_dwordx4 v142, v[56:59], s[76:77] offset:64
	global_load_dwordx2 v[224:225], v194, s[22:23] offset:288
	global_load_dwordx4 v[220:223], v144, s[48:49] offset:576
	v_mul_f32_e32 v52, 0xbfb8aa3b, v52
	v_mul_f32_e32 v53, 0xbfb8aa3b, v53
	v_mul_f32_e32 v54, 0xbfb8aa3b, v54
	v_mul_f32_e32 v55, 0xbfb8aa3b, v55
	v_exp_f32_e32 v52, v52
	v_exp_f32_e32 v53, v53
	v_exp_f32_e32 v54, v54
	v_exp_f32_e32 v55, v55
	v_add_f32_e32 v52, 1.0, v52
	v_add_f32_e32 v53, 1.0, v53
	v_add_f32_e32 v54, 1.0, v54
	v_add_f32_e32 v55, 1.0, v55
	v_rcp_f32_e32 v52, v52
	v_rcp_f32_e32 v53, v53
	v_rcp_f32_e32 v54, v54
	v_rcp_f32_e32 v55, v55
	s_waitcnt vmcnt(27)
	v_lshlrev_b32_e32 v140, 16, v230
	v_and_b32_e32 v141, 0xffff0000, v230
	v_lshlrev_b32_e32 v230, 16, v231
	v_and_b32_e32 v231, 0xffff0000, v231
	v_pk_mul_f32 v[140:141], v[140:141], s[74:75] op_sel_hi:[1,0]
	v_pk_mul_f32 v[230:231], v[230:231], s[74:75] op_sel_hi:[1,0]
	v_pk_fma_f32 v[52:53], v[52:53], v[226:227], v[140:141]
	v_pk_fma_f32 v[54:55], v[54:55], v[228:229], v[230:231]
	global_store_dwordx4 v142, v[52:55], s[76:77] offset:512
	v_add_u32_e32 v145, 0x160000, v139
	v_add_u32_e32 v194, 0xb0000, v138
	global_load_dwordx2 v[230:231], v194, s[22:23] offset:0
	global_load_dwordx4 v[226:229], v145, s[48:49] offset:0
	v_mul_f32_e32 v48, 0xbfb8aa3b, v48
	v_mul_f32_e32 v49, 0xbfb8aa3b, v49
	v_mul_f32_e32 v50, 0xbfb8aa3b, v50
	v_mul_f32_e32 v51, 0xbfb8aa3b, v51
	v_exp_f32_e32 v48, v48
	v_exp_f32_e32 v49, v49
	v_exp_f32_e32 v50, v50
	v_exp_f32_e32 v51, v51
	v_add_f32_e32 v48, 1.0, v48
	v_add_f32_e32 v49, 1.0, v49
	v_add_f32_e32 v50, 1.0, v50
	v_add_f32_e32 v51, 1.0, v51
	v_rcp_f32_e32 v48, v48
	v_rcp_f32_e32 v49, v49
	v_rcp_f32_e32 v50, v50
	v_rcp_f32_e32 v51, v51
	s_waitcnt vmcnt(27)
	v_lshlrev_b32_e32 v140, 16, v236
	v_and_b32_e32 v141, 0xffff0000, v236
	v_lshlrev_b32_e32 v236, 16, v237
	v_and_b32_e32 v237, 0xffff0000, v237
	v_pk_mul_f32 v[140:141], v[140:141], s[74:75] op_sel_hi:[1,0]
	v_pk_mul_f32 v[236:237], v[236:237], s[74:75] op_sel_hi:[1,0]
	v_pk_fma_f32 v[48:49], v[48:49], v[232:233], v[140:141]
	v_pk_fma_f32 v[50:51], v[50:51], v[234:235], v[236:237]
	global_store_dwordx4 v142, v[48:51], s[76:77] offset:576
	global_load_dwordx2 v[236:237], v194, s[22:23] offset:32
	global_load_dwordx4 v[232:235], v145, s[48:49] offset:64
	v_mul_f32_e32 v44, 0xbfb8aa3b, v44
	v_mul_f32_e32 v45, 0xbfb8aa3b, v45
	v_mul_f32_e32 v46, 0xbfb8aa3b, v46
	v_mul_f32_e32 v47, 0xbfb8aa3b, v47
	v_exp_f32_e32 v44, v44
	v_exp_f32_e32 v45, v45
	v_exp_f32_e32 v46, v46
	v_exp_f32_e32 v47, v47
	v_add_f32_e32 v44, 1.0, v44
	v_add_f32_e32 v45, 1.0, v45
	v_add_f32_e32 v46, 1.0, v46
	v_add_f32_e32 v47, 1.0, v47
	v_rcp_f32_e32 v44, v44
	v_rcp_f32_e32 v45, v45
	v_rcp_f32_e32 v46, v46
	v_rcp_f32_e32 v47, v47
	s_waitcnt vmcnt(27)
	v_lshlrev_b32_e32 v140, 16, v154
	v_and_b32_e32 v141, 0xffff0000, v154
	v_lshlrev_b32_e32 v154, 16, v155
	v_and_b32_e32 v155, 0xffff0000, v155
	v_pk_mul_f32 v[140:141], v[140:141], s[74:75] op_sel_hi:[1,0]
	v_pk_mul_f32 v[154:155], v[154:155], s[74:75] op_sel_hi:[1,0]
	v_pk_fma_f32 v[44:45], v[44:45], v[150:151], v[140:141]
	v_pk_fma_f32 v[46:47], v[46:47], v[152:153], v[154:155]
	global_store_dwordx4 v143, v[44:47], s[76:77] offset:0
	global_load_dwordx2 v[154:155], v194, s[22:23] offset:256
	global_load_dwordx4 v[150:153], v145, s[48:49] offset:512
	v_mul_f32_e32 v40, 0xbfb8aa3b, v40
	v_mul_f32_e32 v41, 0xbfb8aa3b, v41
	v_mul_f32_e32 v42, 0xbfb8aa3b, v42
	v_mul_f32_e32 v43, 0xbfb8aa3b, v43
	v_exp_f32_e32 v40, v40
	v_exp_f32_e32 v41, v41
	v_exp_f32_e32 v42, v42
	v_exp_f32_e32 v43, v43
	v_add_f32_e32 v40, 1.0, v40
	v_add_f32_e32 v41, 1.0, v41
	v_add_f32_e32 v42, 1.0, v42
	v_add_f32_e32 v43, 1.0, v43
	v_rcp_f32_e32 v40, v40
	v_rcp_f32_e32 v41, v41
	v_rcp_f32_e32 v42, v42
	v_rcp_f32_e32 v43, v43
	s_waitcnt vmcnt(27)
	v_lshlrev_b32_e32 v140, 16, v160
	v_and_b32_e32 v141, 0xffff0000, v160
	v_lshlrev_b32_e32 v160, 16, v161
	v_and_b32_e32 v161, 0xffff0000, v161
	v_pk_mul_f32 v[140:141], v[140:141], s[74:75] op_sel_hi:[1,0]
	v_pk_mul_f32 v[160:161], v[160:161], s[74:75] op_sel_hi:[1,0]
	v_pk_fma_f32 v[40:41], v[40:41], v[156:157], v[140:141]
	v_pk_fma_f32 v[42:43], v[42:43], v[158:159], v[160:161]
	global_store_dwordx4 v143, v[40:43], s[76:77] offset:64
	global_load_dwordx2 v[160:161], v194, s[22:23] offset:288
	global_load_dwordx4 v[156:159], v145, s[48:49] offset:576
	v_mul_f32_e32 v36, 0xbfb8aa3b, v36
	v_mul_f32_e32 v37, 0xbfb8aa3b, v37
	v_mul_f32_e32 v38, 0xbfb8aa3b, v38
	v_mul_f32_e32 v39, 0xbfb8aa3b, v39
	v_exp_f32_e32 v36, v36
	v_exp_f32_e32 v37, v37
	v_exp_f32_e32 v38, v38
	v_exp_f32_e32 v39, v39
	v_add_f32_e32 v36, 1.0, v36
	v_add_f32_e32 v37, 1.0, v37
	v_add_f32_e32 v38, 1.0, v38
	v_add_f32_e32 v39, 1.0, v39
	v_rcp_f32_e32 v36, v36
	v_rcp_f32_e32 v37, v37
	v_rcp_f32_e32 v38, v38
	v_rcp_f32_e32 v39, v39
	s_waitcnt vmcnt(27)
	v_lshlrev_b32_e32 v140, 16, v180
	v_and_b32_e32 v141, 0xffff0000, v180
	v_lshlrev_b32_e32 v180, 16, v181
	v_and_b32_e32 v181, 0xffff0000, v181
	v_pk_mul_f32 v[140:141], v[140:141], s[74:75] op_sel_hi:[1,0]
	v_pk_mul_f32 v[180:181], v[180:181], s[74:75] op_sel_hi:[1,0]
	v_pk_fma_f32 v[36:37], v[36:37], v[176:177], v[140:141]
	v_pk_fma_f32 v[38:39], v[38:39], v[178:179], v[180:181]
	global_store_dwordx4 v143, v[36:39], s[76:77] offset:512
	v_mul_f32_e32 v32, 0xbfb8aa3b, v32
	v_mul_f32_e32 v33, 0xbfb8aa3b, v33
	v_mul_f32_e32 v34, 0xbfb8aa3b, v34
	v_mul_f32_e32 v35, 0xbfb8aa3b, v35
	v_exp_f32_e32 v32, v32
	v_exp_f32_e32 v33, v33
	v_exp_f32_e32 v34, v34
	v_exp_f32_e32 v35, v35
	v_add_f32_e32 v32, 1.0, v32
	v_add_f32_e32 v33, 1.0, v33
	v_add_f32_e32 v34, 1.0, v34
	v_add_f32_e32 v35, 1.0, v35
	v_rcp_f32_e32 v32, v32
	v_rcp_f32_e32 v33, v33
	v_rcp_f32_e32 v34, v34
	v_rcp_f32_e32 v35, v35
	s_waitcnt vmcnt(25)
	v_lshlrev_b32_e32 v140, 16, v186
	v_and_b32_e32 v141, 0xffff0000, v186
	v_lshlrev_b32_e32 v186, 16, v187
	v_and_b32_e32 v187, 0xffff0000, v187
	v_pk_mul_f32 v[140:141], v[140:141], s[74:75] op_sel_hi:[1,0]
	v_pk_mul_f32 v[186:187], v[186:187], s[74:75] op_sel_hi:[1,0]
	v_pk_fma_f32 v[32:33], v[32:33], v[182:183], v[140:141]
	v_pk_fma_f32 v[34:35], v[34:35], v[184:185], v[186:187]
	global_store_dwordx4 v143, v[32:35], s[76:77] offset:576
	v_mul_f32_e32 v28, 0xbfb8aa3b, v28
	v_mul_f32_e32 v29, 0xbfb8aa3b, v29
	v_mul_f32_e32 v30, 0xbfb8aa3b, v30
	v_mul_f32_e32 v31, 0xbfb8aa3b, v31
	v_exp_f32_e32 v28, v28
	v_exp_f32_e32 v29, v29
	v_exp_f32_e32 v30, v30
	v_exp_f32_e32 v31, v31
	v_add_f32_e32 v28, 1.0, v28
	v_add_f32_e32 v29, 1.0, v29
	v_add_f32_e32 v30, 1.0, v30
	v_add_f32_e32 v31, 1.0, v31
	v_rcp_f32_e32 v28, v28
	v_rcp_f32_e32 v29, v29
	v_rcp_f32_e32 v30, v30
	v_rcp_f32_e32 v31, v31
	s_waitcnt vmcnt(23)
	v_lshlrev_b32_e32 v140, 16, v192
	v_and_b32_e32 v141, 0xffff0000, v192
	v_lshlrev_b32_e32 v192, 16, v193
	v_and_b32_e32 v193, 0xffff0000, v193
	v_pk_mul_f32 v[140:141], v[140:141], s[74:75] op_sel_hi:[1,0]
	v_pk_mul_f32 v[192:193], v[192:193], s[74:75] op_sel_hi:[1,0]
	v_pk_fma_f32 v[28:29], v[28:29], v[188:189], v[140:141]
	v_pk_fma_f32 v[30:31], v[30:31], v[190:191], v[192:193]
	global_store_dwordx4 v144, v[28:31], s[76:77] offset:0
	v_mul_f32_e32 v24, 0xbfb8aa3b, v24
	v_mul_f32_e32 v25, 0xbfb8aa3b, v25
	v_mul_f32_e32 v26, 0xbfb8aa3b, v26
	v_mul_f32_e32 v27, 0xbfb8aa3b, v27
	v_exp_f32_e32 v24, v24
	v_exp_f32_e32 v25, v25
	v_exp_f32_e32 v26, v26
	v_exp_f32_e32 v27, v27
	v_add_f32_e32 v24, 1.0, v24
	v_add_f32_e32 v25, 1.0, v25
	v_add_f32_e32 v26, 1.0, v26
	v_add_f32_e32 v27, 1.0, v27
	v_rcp_f32_e32 v24, v24
	v_rcp_f32_e32 v25, v25
	v_rcp_f32_e32 v26, v26
	v_rcp_f32_e32 v27, v27
	s_waitcnt vmcnt(21)
	v_lshlrev_b32_e32 v140, 16, v212
	v_and_b32_e32 v141, 0xffff0000, v212
	v_lshlrev_b32_e32 v212, 16, v213
	v_and_b32_e32 v213, 0xffff0000, v213
	v_pk_mul_f32 v[140:141], v[140:141], s[74:75] op_sel_hi:[1,0]
	v_pk_mul_f32 v[212:213], v[212:213], s[74:75] op_sel_hi:[1,0]
	v_pk_fma_f32 v[24:25], v[24:25], v[208:209], v[140:141]
	v_pk_fma_f32 v[26:27], v[26:27], v[210:211], v[212:213]
	global_store_dwordx4 v144, v[24:27], s[76:77] offset:64
	v_mul_f32_e32 v20, 0xbfb8aa3b, v20
	v_mul_f32_e32 v21, 0xbfb8aa3b, v21
	v_mul_f32_e32 v22, 0xbfb8aa3b, v22
	v_mul_f32_e32 v23, 0xbfb8aa3b, v23
	v_exp_f32_e32 v20, v20
	v_exp_f32_e32 v21, v21
	v_exp_f32_e32 v22, v22
	v_exp_f32_e32 v23, v23
	v_add_f32_e32 v20, 1.0, v20
	v_add_f32_e32 v21, 1.0, v21
	v_add_f32_e32 v22, 1.0, v22
	v_add_f32_e32 v23, 1.0, v23
	v_rcp_f32_e32 v20, v20
	v_rcp_f32_e32 v21, v21
	v_rcp_f32_e32 v22, v22
	v_rcp_f32_e32 v23, v23
	s_waitcnt vmcnt(19)
	v_lshlrev_b32_e32 v140, 16, v218
	v_and_b32_e32 v141, 0xffff0000, v218
	v_lshlrev_b32_e32 v218, 16, v219
	v_and_b32_e32 v219, 0xffff0000, v219
	v_pk_mul_f32 v[140:141], v[140:141], s[74:75] op_sel_hi:[1,0]
	v_pk_mul_f32 v[218:219], v[218:219], s[74:75] op_sel_hi:[1,0]
	v_pk_fma_f32 v[20:21], v[20:21], v[214:215], v[140:141]
	v_pk_fma_f32 v[22:23], v[22:23], v[216:217], v[218:219]
	global_store_dwordx4 v144, v[20:23], s[76:77] offset:512
	v_mul_f32_e32 v16, 0xbfb8aa3b, v16
	v_mul_f32_e32 v17, 0xbfb8aa3b, v17
	v_mul_f32_e32 v18, 0xbfb8aa3b, v18
	v_mul_f32_e32 v19, 0xbfb8aa3b, v19
	v_exp_f32_e32 v16, v16
	v_exp_f32_e32 v17, v17
	v_exp_f32_e32 v18, v18
	v_exp_f32_e32 v19, v19
	v_add_f32_e32 v16, 1.0, v16
	v_add_f32_e32 v17, 1.0, v17
	v_add_f32_e32 v18, 1.0, v18
	v_add_f32_e32 v19, 1.0, v19
	v_rcp_f32_e32 v16, v16
	v_rcp_f32_e32 v17, v17
	v_rcp_f32_e32 v18, v18
	v_rcp_f32_e32 v19, v19
	s_waitcnt vmcnt(17)
	v_lshlrev_b32_e32 v140, 16, v224
	v_and_b32_e32 v141, 0xffff0000, v224
	v_lshlrev_b32_e32 v224, 16, v225
	v_and_b32_e32 v225, 0xffff0000, v225
	v_pk_mul_f32 v[140:141], v[140:141], s[74:75] op_sel_hi:[1,0]
	v_pk_mul_f32 v[224:225], v[224:225], s[74:75] op_sel_hi:[1,0]
	v_pk_fma_f32 v[16:17], v[16:17], v[220:221], v[140:141]
	v_pk_fma_f32 v[18:19], v[18:19], v[222:223], v[224:225]
	global_store_dwordx4 v144, v[16:19], s[76:77] offset:576
	v_mul_f32_e32 v12, 0xbfb8aa3b, v12
	v_mul_f32_e32 v13, 0xbfb8aa3b, v13
	v_mul_f32_e32 v14, 0xbfb8aa3b, v14
	v_mul_f32_e32 v15, 0xbfb8aa3b, v15
	v_exp_f32_e32 v12, v12
	v_exp_f32_e32 v13, v13
	v_exp_f32_e32 v14, v14
	v_exp_f32_e32 v15, v15
	v_add_f32_e32 v12, 1.0, v12
	v_add_f32_e32 v13, 1.0, v13
	v_add_f32_e32 v14, 1.0, v14
	v_add_f32_e32 v15, 1.0, v15
	v_rcp_f32_e32 v12, v12
	v_rcp_f32_e32 v13, v13
	v_rcp_f32_e32 v14, v14
	v_rcp_f32_e32 v15, v15
	s_waitcnt vmcnt(15)
	v_lshlrev_b32_e32 v140, 16, v230
	v_and_b32_e32 v141, 0xffff0000, v230
	v_lshlrev_b32_e32 v230, 16, v231
	v_and_b32_e32 v231, 0xffff0000, v231
	v_pk_mul_f32 v[140:141], v[140:141], s[74:75] op_sel_hi:[1,0]
	v_pk_mul_f32 v[230:231], v[230:231], s[74:75] op_sel_hi:[1,0]
	v_pk_fma_f32 v[12:13], v[12:13], v[226:227], v[140:141]
	v_pk_fma_f32 v[14:15], v[14:15], v[228:229], v[230:231]
	global_store_dwordx4 v145, v[12:15], s[76:77] offset:0
	v_mul_f32_e32 v8, 0xbfb8aa3b, v8
	v_mul_f32_e32 v9, 0xbfb8aa3b, v9
	v_mul_f32_e32 v10, 0xbfb8aa3b, v10
	v_mul_f32_e32 v11, 0xbfb8aa3b, v11
	v_exp_f32_e32 v8, v8
	v_exp_f32_e32 v9, v9
	v_exp_f32_e32 v10, v10
	v_exp_f32_e32 v11, v11
	v_add_f32_e32 v8, 1.0, v8
	v_add_f32_e32 v9, 1.0, v9
	v_add_f32_e32 v10, 1.0, v10
	v_add_f32_e32 v11, 1.0, v11
	v_rcp_f32_e32 v8, v8
	v_rcp_f32_e32 v9, v9
	v_rcp_f32_e32 v10, v10
	v_rcp_f32_e32 v11, v11
	s_waitcnt vmcnt(13)
	v_lshlrev_b32_e32 v140, 16, v236
	v_and_b32_e32 v141, 0xffff0000, v236
	v_lshlrev_b32_e32 v236, 16, v237
	v_and_b32_e32 v237, 0xffff0000, v237
	v_pk_mul_f32 v[140:141], v[140:141], s[74:75] op_sel_hi:[1,0]
	v_pk_mul_f32 v[236:237], v[236:237], s[74:75] op_sel_hi:[1,0]
	v_pk_fma_f32 v[8:9], v[8:9], v[232:233], v[140:141]
	v_pk_fma_f32 v[10:11], v[10:11], v[234:235], v[236:237]
	global_store_dwordx4 v145, v[8:11], s[76:77] offset:64
	v_mul_f32_e32 v4, 0xbfb8aa3b, v4
	v_mul_f32_e32 v5, 0xbfb8aa3b, v5
	v_mul_f32_e32 v6, 0xbfb8aa3b, v6
	v_mul_f32_e32 v7, 0xbfb8aa3b, v7
	v_exp_f32_e32 v4, v4
	v_exp_f32_e32 v5, v5
	v_exp_f32_e32 v6, v6
	v_exp_f32_e32 v7, v7
	v_add_f32_e32 v4, 1.0, v4
	v_add_f32_e32 v5, 1.0, v5
	v_add_f32_e32 v6, 1.0, v6
	v_add_f32_e32 v7, 1.0, v7
	v_rcp_f32_e32 v4, v4
	v_rcp_f32_e32 v5, v5
	v_rcp_f32_e32 v6, v6
	v_rcp_f32_e32 v7, v7
	s_waitcnt vmcnt(11)
	v_lshlrev_b32_e32 v140, 16, v154
	v_and_b32_e32 v141, 0xffff0000, v154
	v_lshlrev_b32_e32 v154, 16, v155
	v_and_b32_e32 v155, 0xffff0000, v155
	v_pk_mul_f32 v[140:141], v[140:141], s[74:75] op_sel_hi:[1,0]
	v_pk_mul_f32 v[154:155], v[154:155], s[74:75] op_sel_hi:[1,0]
	v_pk_fma_f32 v[4:5], v[4:5], v[150:151], v[140:141]
	v_pk_fma_f32 v[6:7], v[6:7], v[152:153], v[154:155]
	global_store_dwordx4 v145, v[4:7], s[76:77] offset:512
	v_mul_f32_e32 v0, 0xbfb8aa3b, v0
	v_mul_f32_e32 v1, 0xbfb8aa3b, v1
	v_mul_f32_e32 v2, 0xbfb8aa3b, v2
	v_mul_f32_e32 v3, 0xbfb8aa3b, v3
	v_exp_f32_e32 v0, v0
	v_exp_f32_e32 v1, v1
	v_exp_f32_e32 v2, v2
	v_exp_f32_e32 v3, v3
	v_add_f32_e32 v0, 1.0, v0
	v_add_f32_e32 v1, 1.0, v1
	v_add_f32_e32 v2, 1.0, v2
	v_add_f32_e32 v3, 1.0, v3
	v_rcp_f32_e32 v0, v0
	v_rcp_f32_e32 v1, v1
	v_rcp_f32_e32 v2, v2
	v_rcp_f32_e32 v3, v3
	s_waitcnt vmcnt(9)
	v_lshlrev_b32_e32 v140, 16, v160
	v_and_b32_e32 v141, 0xffff0000, v160
	v_lshlrev_b32_e32 v160, 16, v161
	v_and_b32_e32 v161, 0xffff0000, v161
	v_pk_mul_f32 v[140:141], v[140:141], s[74:75] op_sel_hi:[1,0]
	v_pk_mul_f32 v[160:161], v[160:161], s[74:75] op_sel_hi:[1,0]
	v_pk_fma_f32 v[0:1], v[0:1], v[156:157], v[140:141]
	v_pk_fma_f32 v[2:3], v[2:3], v[158:159], v[160:161]
	global_store_dwordx4 v145, v[0:3], s[76:77] offset:576
	s_mov_b64 s[22:23], s[16:17]
	s_mov_b64 s[20:21], s[14:15]
	s_and_b64 vcc, exec, s[8:9]
	s_cbranch_vccz .LBB0_95
	s_waitcnt vmcnt(0)
	s_cmpk_gt_u32 s1, 0xff
	s_cbranch_scc1 .LBB0_106
	s_barrier
